# gla scan: q.S fragment reads double-buffered under the MFMA pairs (one 16-row block)
# baseline (speedup 1.0000x reference)
; #define LAS __attribute__((address_space(3)))
; DI void gla_scan_phase(const PZ& p, LAS unsigned char* lds, int tid, int wave, int lane_in) {
;     ...
;                 const int tt = wave >> 1, s0 = (wave & 1) * 2;
;                 f32x4 aacc[2]; aacc[0] = (f32x4){0.f, 0.f, 0.f, 0.f}; aacc[1] = aacc[0];
; #pragma unroll
;                 for (int ks = 0; ks < 4; ++ks) {
;                     const bf16x8 a = *(const LAS bf16x8*)(Qd + (tt * 16 + l15) * 136 + ks * 32 + g * 8);
; #pragma unroll
;                     for (int n2 = 0; n2 < 2; ++n2) { const bf16x8 bfr = *(const LAS bf16x8*)(Ki + ((s0 + n2) * 16 + l15) * 136 + ks * 32 + g * 8); aacc[n2] = MFMA16(a, bfr, aacc[n2]); }
;                 }
; #pragma unroll
;                 for (int n2 = 0; n2 < 2; ++n2)
; #pragma unroll
;                     for (int j = 0; j < 4; ++j) { const int t = tt * 16 + g * 4 + j, s2 = (s0 + n2) * 16 + l15; Ab[t * 72 + s2] = f2bf(s2 <= t ? aacc[n2][j] : 0.f); }
;             }
;             __syncthreads();
;             bf16x8 sfr[4][2];
; #pragma unroll
;             for (int kp = 0; kp < 4; ++kp)
; #pragma unroll
;                 for (int n2 = 0; n2 < 2; ++n2) {
;                     const f32x4 x0 = S[2 * kp][n2], x1 = S[2 * kp + 1][n2];
;                     sfr[kp][n2] = mk8((u32x2){cvtpk(x0.x, x0.y), cvtpk(x0.z, x0.w)}, (u32x2){cvtpk(x1.x, x1.y), cvtpk(x1.z, x1.w)});
;                 }
; #pragma unroll
;             for (int mt = 0; mt < 4; ++mt) {
;                 f32x4 oacc[2]; oacc[0] = (f32x4){0.f, 0.f, 0.f, 0.f}; oacc[1] = oacc[0];
; #pragma unroll
;                 for (int ks = 0; ks < 2; ++ks) {
;                     const bf16x8 a = *(const LAS bf16x8*)(Ab + (mt * 16 + l15) * 72 + ks * 32 + g * 8);
; #pragma unroll
;                     for (int n2 = 0; n2 < 2; ++n2) { const bf16x8 bfr = *(const LAS bf16x8*)(Vt + (wave * 32 + n2 * 16 + l15) * 72 + ks * 32 + g * 8); oacc[n2] = MFMA16(a, bfr, oacc[n2]); }
;                 }
; #pragma unroll
;                 for (int kp = 0; kp < 4; ++kp) {
;                     const bf16x8 a = mk8(*(const LAS u32x2*)(Qd + (mt * 16 + l15) * 136 + (2 * kp) * 16 + g * 4), *(const LAS u32x2*)(Qd + (mt * 16 + l15) * 136 + (2 * kp + 1) * 16 + g * 4));
; #pragma unroll
;                     for (int n2 = 0; n2 < 2; ++n2) oacc[n2] = MFMA16(a, sfr[kp][n2], oacc[n2]);
;                 }
.LBB0_122:
	s_sub_i32 s3, s52, 64
	s_cmp_gt_u32 s35, 3
	s_cselect_b32 s8, s64, 0xff
	s_add_i32 s8, s8, s53
	s_add_i32 s12, s8, 64
	s_and_b64 s[8:9], s[48:49], exec
	s_cselect_b32 s3, s3, s12
	s_ashr_i32 s8, s3, 31
	v_and_b32_e32 v212, 15, v92
	v_and_b32_e32 v89, -16, v92
	s_add_u32 s36, s50, s3
	v_or_b32_e32 v88, s5, v212
	v_add_u32_e32 v144, 0, v89
	s_addc_u32 s37, s51, s8
	v_mad_u64_u32 v[104:105], s[8:9], v88, s65, v[144:145]
	s_waitcnt lgkmcnt(0)
	s_barrier
	ds_read_b128 v[88:91], v104
	v_or_b32_e32 v105, s4, v212
	v_mad_u32_u24 v106, v105, s65, v144
	v_ashrrev_i32_e32 v2, 4, v92
	ds_read_b128 v[92:95], v106 offset:17408
	ds_read_b128 v[96:99], v106 offset:21760
	s_waitcnt lgkmcnt(1)
	v_mfma_f32_16x16x32_bf16 v[92:95], v[88:91], v[92:95], 0
	v_lshlrev_b32_e32 v213, 3, v2
	v_lshlrev_b32_e32 v2, 2, v2
	v_or_b32_e32 v107, 16, v105
	s_waitcnt lgkmcnt(0)
	v_mfma_f32_16x16x32_bf16 v[88:91], v[88:91], v[96:99], 0
	ds_read_b128 v[96:99], v104 offset:64
	ds_read_b128 v[100:103], v106 offset:17472
	v_mad_u32_u24 v199, v212, s33, v144
	v_or_b32_e32 v142, s20, v212
	s_waitcnt lgkmcnt(0)
	v_mfma_f32_16x16x32_bf16 v[92:95], v[96:99], v[100:103], v[92:95]
	ds_read_b128 v[100:103], v106 offset:21824
	v_mad_u64_u32 v[142:143], s[8:9], v142, s33, v[144:145]
	s_waitcnt lgkmcnt(0)
	v_mfma_f32_16x16x32_bf16 v[88:91], v[96:99], v[100:103], v[88:91]
	ds_read_b128 v[96:99], v104 offset:128
	ds_read_b128 v[100:103], v106 offset:17536
	v_mul_u32_u24_e32 v143, 0x110, v212
	v_add3_u32 v143, 0, v143, v213
	s_waitcnt lgkmcnt(0)
	v_mfma_f32_16x16x32_bf16 v[92:95], v[96:99], v[100:103], v[92:95]
	ds_read_b128 v[100:103], v106 offset:21888
	v_cvt_pk_bf16_f32 v108, v20, v21
	v_cvt_pk_bf16_f32 v109, v22, v23
	s_waitcnt lgkmcnt(0)
	v_mfma_f32_16x16x32_bf16 v[88:91], v[96:99], v[100:103], v[88:91]
	ds_read_b128 v[96:99], v104 offset:192
	ds_read_b128 v[100:103], v106 offset:17600
	v_cvt_pk_bf16_f32 v104, v16, v17
	v_cvt_pk_bf16_f32 v110, v52, v53
	s_waitcnt lgkmcnt(0)
	v_mfma_f32_16x16x32_bf16 v[92:95], v[96:99], v[100:103], v[92:95]
	ds_read_b128 v[100:103], v106 offset:21952
	v_cvt_pk_bf16_f32 v106, v48, v49
	v_cvt_pk_bf16_f32 v111, v54, v55
	s_waitcnt lgkmcnt(0)
	v_mfma_f32_16x16x32_bf16 v[88:91], v[96:99], v[100:103], v[88:91]
	v_add_u32_e32 v96, s5, v2
	v_lshlrev_b32_e32 v97, 1, v105
	s_nop 0
	v_cvt_pk_bf16_f32 v92, v92, s0
	v_cmp_le_i32_e32 vcc, v105, v96
	v_mul_lo_u32 v98, v96, s33
	v_add3_u32 v97, 0, v97, v98
	v_cndmask_b32_e32 v92, 0, v92, vcc
	ds_write_b16 v97, v92 offset:53248
	v_or_b32_e32 v92, 1, v96
	v_cvt_pk_bf16_f32 v93, v93, s0
	v_cmp_le_i32_e32 vcc, v105, v92
	v_cvt_pk_bf16_f32 v94, v94, s0
	v_cvt_pk_bf16_f32 v95, v95, s0
	v_cndmask_b32_e32 v93, 0, v93, vcc
	ds_write_b16 v97, v93 offset:53392
	v_or_b32_e32 v93, 2, v96
	v_cmp_le_i32_e32 vcc, v105, v93
	v_cvt_pk_bf16_f32 v88, v88, s0
	v_cvt_pk_bf16_f32 v98, v32, v33
	v_cndmask_b32_e32 v94, 0, v94, vcc
	ds_write_b16 v97, v94 offset:53536
	v_or_b32_e32 v94, 3, v96
	v_cmp_le_i32_e32 vcc, v105, v94
	v_cvt_pk_bf16_f32 v99, v34, v35
	v_cvt_pk_bf16_f32 v100, v12, v13
	v_cndmask_b32_e32 v95, 0, v95, vcc
	v_cmp_le_i32_e32 vcc, v107, v96
	ds_write_b16 v97, v95 offset:53680
	v_cvt_pk_bf16_f32 v95, v46, v47
	v_cndmask_b32_e32 v88, 0, v88, vcc
	ds_write_b16 v97, v88 offset:53280
	v_cvt_pk_bf16_f32 v88, v89, s0
	v_cmp_le_i32_e32 vcc, v107, v92
	v_cvt_pk_bf16_f32 v89, v82, v83
	v_cvt_pk_bf16_f32 v92, v84, v85
	v_cndmask_b32_e32 v88, 0, v88, vcc
	ds_write_b16 v97, v88 offset:53424
	v_cvt_pk_bf16_f32 v88, v90, s0
	v_cmp_le_i32_e32 vcc, v107, v93
	v_cvt_pk_bf16_f32 v90, v40, v41
	v_cvt_pk_bf16_f32 v93, v86, v87
	v_cndmask_b32_e32 v88, 0, v88, vcc
	ds_write_b16 v97, v88 offset:53568
	v_cvt_pk_bf16_f32 v88, v91, s0
	v_cmp_le_i32_e32 vcc, v107, v94
	v_cvt_pk_bf16_f32 v91, v42, v43
	v_cvt_pk_bf16_f32 v94, v44, v45
	v_cndmask_b32_e32 v88, 0, v88, vcc
	ds_write_b16 v97, v88 offset:53712
	s_waitcnt lgkmcnt(0)
	s_barrier
	ds_read_b128 v[120:123], v199 offset:53248
	ds_read_b128 v[214:217], v142 offset:62464
	ds_read_b128 v[218:221], v142 offset:64768
	s_waitcnt lgkmcnt(1)
	v_mfma_f32_16x16x32_bf16 v[214:217], v[120:123], v[214:217], 0
	v_cvt_pk_bf16_f32 v88, v80, v81
	v_cvt_pk_bf16_f32 v96, v8, v9
	v_cvt_pk_bf16_f32 v97, v10, v11
	s_waitcnt lgkmcnt(0)
	v_mfma_f32_16x16x32_bf16 v[120:123], v[120:123], v[218:221], 0
	ds_read_b128 v[218:221], v199 offset:53312
	ds_read_b128 v[222:225], v142 offset:62528
	v_cvt_pk_bf16_f32 v101, v14, v15
	v_cvt_pk_bf16_f32 v102, v36, v37
	s_waitcnt lgkmcnt(0)
	v_mfma_f32_16x16x32_bf16 v[214:217], v[218:221], v[222:225], v[214:217]
	ds_read_b128 v[222:225], v142 offset:64832
	v_cvt_pk_bf16_f32 v103, v38, v39
	v_cvt_pk_bf16_f32 v105, v18, v19
	s_waitcnt lgkmcnt(0)
	v_mfma_f32_16x16x32_bf16 v[120:123], v[218:221], v[222:225], v[120:123]
	ds_read2_b64 v[218:221], v143 offset1:4
	ds_read2_b64 v[236:239], v143 offset0:8 offset1:12
	v_cvt_pk_bf16_f32 v107, v50, v51
	v_mul_lo_u32 v146, v2, s34
	s_waitcnt lgkmcnt(1)
	v_mfma_f32_16x16x32_bf16 v[214:217], v[218:221], v[88:91], v[214:217]
	v_ashrrev_i32_e32 v147, 31, v146
	v_lshl_add_u64 v[160:161], s[36:37], 0, v[146:147]
	v_cvt_pk_bf16_f32 v112, v24, v25
	v_mfma_f32_16x16x32_bf16 v[120:123], v[218:221], v[92:95], v[120:123]
	ds_read2_b64 v[218:221], v143 offset0:16 offset1:20
	v_cvt_pk_bf16_f32 v113, v26, v27
	v_cvt_pk_bf16_f32 v114, v56, v57
	s_waitcnt lgkmcnt(1)
	v_mfma_f32_16x16x32_bf16 v[214:217], v[236:239], v[96:99], v[214:217]
	v_cvt_pk_bf16_f32 v115, v58, v59
	v_lshlrev_b64 v[160:161], 13, v[160:161]
	v_lshl_add_u64 v[160:161], s[28:29], 0, v[160:161]
	v_mfma_f32_16x16x32_bf16 v[120:123], v[236:239], v[100:103], v[120:123]
	ds_read2_b64 v[236:239], v143 offset0:24 offset1:28
	s_lshl_b64 s[42:43], s[20:21], 1
	v_lshl_add_u64 v[160:161], v[160:161], 0, s[42:43]
	s_waitcnt lgkmcnt(1)
; #define LAS __attribute__((address_space(3)))
; DI unsigned short f2bf(float f) { return (unsigned short)(cvtpk(f, f) & 0xffffu); }
; #define MFMA16(a, b, c) __builtin_amdgcn_mfma_f32_16x16x32_bf16((a), (b), (c), 0, 0, 0)
; DI void gla_scan_phase(const PZ& p, LAS unsigned char* lds, int tid, int wave, int lane_in) {
;     ...
;             for (int mt = 0; mt < 4; ++mt) {
;                 f32x4 oacc[2]; oacc[0] = (f32x4){0.f, 0.f, 0.f, 0.f}; oacc[1] = oacc[0];
; #pragma unroll
;                 for (int ks = 0; ks < 2; ++ks) {
;                     const bf16x8 a = *(const LAS bf16x8*)(Ab + (mt * 16 + l15) * 72 + ks * 32 + g * 8);
; #pragma unroll
;                     for (int n2 = 0; n2 < 2; ++n2) { const bf16x8 bfr = *(const LAS bf16x8*)(Vt + (wave * 32 + n2 * 16 + l15) * 72 + ks * 32 + g * 8); oacc[n2] = MFMA16(a, bfr, oacc[n2]); }
;                 }
; #pragma unroll
;                 for (int kp = 0; kp < 4; ++kp) {
;                     const bf16x8 a = mk8(*(const LAS u32x2*)(Qd + (mt * 16 + l15) * 136 + (2 * kp) * 16 + g * 4), *(const LAS u32x2*)(Qd + (mt * 16 + l15) * 136 + (2 * kp + 1) * 16 + g * 4));
; #pragma unroll
;                     for (int n2 = 0; n2 < 2; ++n2) oacc[n2] = MFMA16(a, sfr[kp][n2], oacc[n2]);
;                 }
; #pragma unroll
;                 for (int j = 0; j < 4; ++j) {
;                     const long m = mc0 + sgn * (mt * 16 + g * 4 + j);
; #pragma unroll
;                     for (int n2 = 0; n2 < 2; ++n2) big[m * 4096 + ocol0 + wave * 32 + n2 * 16 + l15] = f2bf(oacc[n2][j]);
;                 }
	v_mfma_f32_16x16x32_bf16 v[214:217], v[218:221], v[104:107], v[214:217]
	v_lshlrev_b32_e32 v2, 1, v212
	v_cvt_pk_bf16_f32 v116, v28, v29
	v_cvt_pk_bf16_f32 v117, v30, v31
	v_mfma_f32_16x16x32_bf16 v[120:123], v[218:221], v[108:111], v[120:123]
	v_cvt_pk_bf16_f32 v118, v60, v61
	v_cvt_pk_bf16_f32 v119, v62, v63
	s_waitcnt lgkmcnt(0)
	v_mfma_f32_16x16x32_bf16 v[214:217], v[236:239], v[112:115], v[214:217]
	v_lshl_add_u64 v[160:161], v[160:161], 0, v[2:3]
	v_add_u32_e32 v146, s34, v146
	v_ashrrev_i32_e32 v147, 31, v146
	v_mfma_f32_16x16x32_bf16 v[120:123], v[236:239], v[116:119], v[120:123]
	v_lshl_add_u64 v[218:219], v[160:161], 0, s[78:79]
	v_add_co_u32_e32 v160, vcc, s97, v160
	s_nop 1
	v_cvt_pk_bf16_f32 v143, v214, s0
	v_addc_co_u32_e32 v161, vcc, 0, v161, vcc
	global_store_short v[160:161], v143, off
	v_lshl_add_u64 v[160:161], s[36:37], 0, v[146:147]
	v_lshlrev_b64 v[160:161], 13, v[160:161]
	v_lshl_add_u64 v[160:161], s[28:29], 0, v[160:161]
	v_lshl_add_u64 v[160:161], v[160:161], 0, s[42:43]
	v_cvt_pk_bf16_f32 v120, v120, s0
	v_lshl_add_u64 v[160:161], v[160:161], 0, v[2:3]
	global_store_short v[218:219], v120, off offset:32
	v_lshl_add_u64 v[218:219], v[160:161], 0, s[78:79]
	v_add_co_u32_e32 v160, vcc, s97, v160
	v_cvt_pk_bf16_f32 v120, v215, s0
	s_nop 0
	v_addc_co_u32_e32 v161, vcc, 0, v161, vcc
	global_store_short v[160:161], v120, off
	v_cvt_pk_bf16_f32 v120, v121, s0
	global_store_short v[218:219], v120, off offset:32
	v_add_u32_e32 v120, s34, v146
	v_ashrrev_i32_e32 v121, 31, v120
	v_lshl_add_u64 v[146:147], s[36:37], 0, v[120:121]
	v_lshlrev_b64 v[146:147], 13, v[146:147]
	v_lshl_add_u64 v[146:147], s[28:29], 0, v[146:147]
	v_lshl_add_u64 v[146:147], v[146:147], 0, s[42:43]
	v_lshl_add_u64 v[146:147], v[146:147], 0, v[2:3]
	v_lshl_add_u64 v[160:161], v[146:147], 0, s[78:79]
	v_add_co_u32_e32 v146, vcc, s97, v146
	v_cvt_pk_bf16_f32 v121, v216, s0
	s_nop 0
	v_addc_co_u32_e32 v147, vcc, 0, v147, vcc
	global_store_short v[146:147], v121, off
	v_add_u32_e32 v146, s34, v120
	v_cvt_pk_bf16_f32 v121, v122, s0
	v_ashrrev_i32_e32 v147, 31, v146
	global_store_short v[160:161], v121, off offset:32
	v_lshl_add_u64 v[120:121], s[36:37], 0, v[146:147]
	v_lshlrev_b64 v[120:121], 13, v[120:121]
	v_lshl_add_u64 v[120:121], s[28:29], 0, v[120:121]
	v_lshl_add_u64 v[120:121], v[120:121], 0, s[42:43]
	v_lshl_add_u64 v[120:121], v[120:121], 0, v[2:3]
	v_lshl_add_u64 v[160:161], v[120:121], 0, s[78:79]
	v_add_co_u32_e32 v120, vcc, s97, v120
	v_cvt_pk_bf16_f32 v122, v217, s0
	s_nop 0
	v_addc_co_u32_e32 v121, vcc, 0, v121, vcc
	global_store_short v[120:121], v122, off
	v_cvt_pk_bf16_f32 v120, v123, s0
	v_or_b32_e32 v147, 16, v212
	global_store_short v[160:161], v120, off offset:32
	v_mad_u32_u24 v143, v147, s33, v144
	ds_read_b128 v[120:123], v143 offset:53248
	ds_read_b128 v[214:217], v142 offset:62464
	ds_read_b128 v[218:221], v142 offset:64768
	s_waitcnt lgkmcnt(1)
	v_mfma_f32_16x16x32_bf16 v[214:217], v[120:123], v[214:217], 0
	v_mul_u32_u24_e32 v147, 0x110, v147
	v_add3_u32 v147, 0, v147, v213
	v_add_u32_e32 v146, s7, v146
	s_waitcnt lgkmcnt(0)
	v_mfma_f32_16x16x32_bf16 v[120:123], v[120:123], v[218:221], 0
	ds_read_b128 v[218:221], v143 offset:53312
	ds_read_b128 v[222:225], v142 offset:62528
	s_waitcnt lgkmcnt(0)
	v_mfma_f32_16x16x32_bf16 v[214:217], v[218:221], v[222:225], v[214:217]
	ds_read_b128 v[222:225], v142 offset:64832
	s_waitcnt lgkmcnt(0)
	v_mfma_f32_16x16x32_bf16 v[120:123], v[218:221], v[222:225], v[120:123]
	ds_read2_b64 v[218:221], v147 offset1:4
	s_waitcnt lgkmcnt(0)
	v_mfma_f32_16x16x32_bf16 v[214:217], v[218:221], v[88:91], v[214:217]
	v_mfma_f32_16x16x32_bf16 v[120:123], v[218:221], v[92:95], v[120:123]
	ds_read2_b64 v[218:221], v147 offset0:8 offset1:12
	s_waitcnt lgkmcnt(0)
	v_mfma_f32_16x16x32_bf16 v[214:217], v[218:221], v[96:99], v[214:217]
	v_mfma_f32_16x16x32_bf16 v[120:123], v[218:221], v[100:103], v[120:123]
	ds_read2_b64 v[218:221], v147 offset0:16 offset1:20
	s_waitcnt lgkmcnt(0)
	v_mfma_f32_16x16x32_bf16 v[214:217], v[218:221], v[104:107], v[214:217]
	v_mfma_f32_16x16x32_bf16 v[120:123], v[218:221], v[108:111], v[120:123]
	ds_read2_b64 v[218:221], v147 offset0:24 offset1:28
	v_ashrrev_i32_e32 v147, 31, v146
	v_lshl_add_u64 v[160:161], s[36:37], 0, v[146:147]
	v_lshlrev_b64 v[160:161], 13, v[160:161]
	s_waitcnt lgkmcnt(0)
; #define LAS __attribute__((address_space(3)))
; DI unsigned short f2bf(float f) { return (unsigned short)(cvtpk(f, f) & 0xffffu); }
; #define MFMA16(a, b, c) __builtin_amdgcn_mfma_f32_16x16x32_bf16((a), (b), (c), 0, 0, 0)
; DI void gla_scan_phase(const PZ& p, LAS unsigned char* lds, int tid, int wave, int lane_in) {
;     ...
;             for (int mt = 0; mt < 4; ++mt) {
;                 f32x4 oacc[2]; oacc[0] = (f32x4){0.f, 0.f, 0.f, 0.f}; oacc[1] = oacc[0];
; #pragma unroll
;                 for (int ks = 0; ks < 2; ++ks) {
;                     const bf16x8 a = *(const LAS bf16x8*)(Ab + (mt * 16 + l15) * 72 + ks * 32 + g * 8);
; #pragma unroll
;                     for (int n2 = 0; n2 < 2; ++n2) { const bf16x8 bfr = *(const LAS bf16x8*)(Vt + (wave * 32 + n2 * 16 + l15) * 72 + ks * 32 + g * 8); oacc[n2] = MFMA16(a, bfr, oacc[n2]); }
;                 }
; #pragma unroll
;                 for (int kp = 0; kp < 4; ++kp) {
;                     const bf16x8 a = mk8(*(const LAS u32x2*)(Qd + (mt * 16 + l15) * 136 + (2 * kp) * 16 + g * 4), *(const LAS u32x2*)(Qd + (mt * 16 + l15) * 136 + (2 * kp + 1) * 16 + g * 4));
; #pragma unroll
;                     for (int n2 = 0; n2 < 2; ++n2) oacc[n2] = MFMA16(a, sfr[kp][n2], oacc[n2]);
;                 }
; #pragma unroll
;                 for (int j = 0; j < 4; ++j) {
;                     const long m = mc0 + sgn * (mt * 16 + g * 4 + j);
; #pragma unroll
;                     for (int n2 = 0; n2 < 2; ++n2) big[m * 4096 + ocol0 + wave * 32 + n2 * 16 + l15] = f2bf(oacc[n2][j]);
;                 }
	v_mfma_f32_16x16x32_bf16 v[214:217], v[218:221], v[112:115], v[214:217]
	v_lshl_add_u64 v[160:161], s[28:29], 0, v[160:161]
	v_lshl_add_u64 v[160:161], v[160:161], 0, s[42:43]
	v_lshl_add_u64 v[160:161], v[160:161], 0, v[2:3]
	v_mfma_f32_16x16x32_bf16 v[120:123], v[218:221], v[116:119], v[120:123]
	v_lshl_add_u64 v[218:219], v[160:161], 0, s[78:79]
	v_add_co_u32_e32 v160, vcc, s97, v160
	s_nop 1
	v_cvt_pk_bf16_f32 v147, v214, s0
	v_addc_co_u32_e32 v161, vcc, 0, v161, vcc
	v_add_u32_e32 v146, s34, v146
	global_store_short v[160:161], v147, off
	v_ashrrev_i32_e32 v147, 31, v146
	v_lshl_add_u64 v[160:161], s[36:37], 0, v[146:147]
	v_lshlrev_b64 v[160:161], 13, v[160:161]
	v_lshl_add_u64 v[160:161], s[28:29], 0, v[160:161]
	v_lshl_add_u64 v[160:161], v[160:161], 0, s[42:43]
	v_cvt_pk_bf16_f32 v120, v120, s0
	v_lshl_add_u64 v[160:161], v[160:161], 0, v[2:3]
	global_store_short v[218:219], v120, off offset:32
	v_lshl_add_u64 v[218:219], v[160:161], 0, s[78:79]
	v_add_co_u32_e32 v160, vcc, s97, v160
	v_cvt_pk_bf16_f32 v120, v215, s0
	s_nop 0
	v_addc_co_u32_e32 v161, vcc, 0, v161, vcc
	global_store_short v[160:161], v120, off
	v_cvt_pk_bf16_f32 v120, v121, s0
	global_store_short v[218:219], v120, off offset:32
	v_add_u32_e32 v120, s34, v146
	v_ashrrev_i32_e32 v121, 31, v120
	v_lshl_add_u64 v[146:147], s[36:37], 0, v[120:121]
	v_lshlrev_b64 v[146:147], 13, v[146:147]
	v_lshl_add_u64 v[146:147], s[28:29], 0, v[146:147]
	v_lshl_add_u64 v[146:147], v[146:147], 0, s[42:43]
	v_lshl_add_u64 v[146:147], v[146:147], 0, v[2:3]
	v_lshl_add_u64 v[160:161], v[146:147], 0, s[78:79]
	v_add_co_u32_e32 v146, vcc, s97, v146
	v_cvt_pk_bf16_f32 v121, v216, s0
	s_nop 0
	v_addc_co_u32_e32 v147, vcc, 0, v147, vcc
	global_store_short v[146:147], v121, off
	v_cvt_pk_bf16_f32 v121, v122, s0
	v_add_u32_e32 v120, s34, v120
	global_store_short v[160:161], v121, off offset:32
	v_ashrrev_i32_e32 v121, 31, v120
	v_lshl_add_u64 v[146:147], s[36:37], 0, v[120:121]
	v_lshlrev_b64 v[146:147], 13, v[146:147]
	v_lshl_add_u64 v[146:147], s[28:29], 0, v[146:147]
	v_lshl_add_u64 v[146:147], v[146:147], 0, s[42:43]
	v_lshl_add_u64 v[146:147], v[146:147], 0, v[2:3]
	v_lshl_add_u64 v[160:161], v[146:147], 0, s[78:79]
	v_add_co_u32_e32 v146, vcc, s97, v146
	v_cvt_pk_bf16_f32 v121, v217, s0
	s_nop 0
	v_addc_co_u32_e32 v147, vcc, 0, v147, vcc
	global_store_short v[146:147], v121, off
	v_cvt_pk_bf16_f32 v121, v123, s0
	v_or_b32_e32 v122, 32, v212
	global_store_short v[160:161], v121, off offset:32
	v_mad_u32_u24 v121, v122, s33, v144
	ds_read_b128 v[214:217], v121 offset:53248
	ds_read_b128 v[218:221], v142 offset:62464
	ds_read_b128 v[222:225], v142 offset:64768
	s_waitcnt lgkmcnt(1)
	v_mfma_f32_16x16x32_bf16 v[218:221], v[214:217], v[218:221], 0
	v_mul_u32_u24_e32 v122, 0x110, v122
	v_add3_u32 v122, 0, v122, v213
	s_waitcnt lgkmcnt(0)
	v_mfma_f32_16x16x32_bf16 v[214:217], v[214:217], v[222:225], 0
	ds_read_b128 v[222:225], v121 offset:53312
	ds_read_b128 v[226:229], v142 offset:62528
	s_waitcnt lgkmcnt(0)
	v_mfma_f32_16x16x32_bf16 v[218:221], v[222:225], v[226:229], v[218:221]
	ds_read_b128 v[226:229], v142 offset:64832
	s_waitcnt lgkmcnt(0)
	v_mfma_f32_16x16x32_bf16 v[214:217], v[222:225], v[226:229], v[214:217]
	ds_read2_b64 v[222:225], v122 offset1:4
	s_waitcnt lgkmcnt(0)
	v_mfma_f32_16x16x32_bf16 v[218:221], v[222:225], v[88:91], v[218:221]
	v_mfma_f32_16x16x32_bf16 v[214:217], v[222:225], v[92:95], v[214:217]
	ds_read2_b64 v[222:225], v122 offset0:8 offset1:12
	s_waitcnt lgkmcnt(0)
	v_mfma_f32_16x16x32_bf16 v[218:221], v[222:225], v[96:99], v[218:221]
	v_mfma_f32_16x16x32_bf16 v[214:217], v[222:225], v[100:103], v[214:217]
	ds_read2_b64 v[222:225], v122 offset0:16 offset1:20
	s_waitcnt lgkmcnt(0)
	v_mfma_f32_16x16x32_bf16 v[218:221], v[222:225], v[104:107], v[218:221]
	v_mfma_f32_16x16x32_bf16 v[214:217], v[222:225], v[108:111], v[214:217]
	ds_read2_b64 v[222:225], v122 offset0:24 offset1:28
	v_add_u32_e32 v122, s7, v120
	v_ashrrev_i32_e32 v123, 31, v122
	v_lshl_add_u64 v[146:147], s[36:37], 0, v[122:123]
	v_lshlrev_b64 v[146:147], 13, v[146:147]
	s_waitcnt lgkmcnt(0)
	v_mfma_f32_16x16x32_bf16 v[218:221], v[222:225], v[112:115], v[218:221]
	v_lshl_add_u64 v[146:147], s[28:29], 0, v[146:147]
	v_lshl_add_u64 v[146:147], v[146:147], 0, s[42:43]
	v_lshl_add_u64 v[146:147], v[146:147], 0, v[2:3]
	v_lshl_add_u64 v[160:161], v[146:147], 0, s[78:79]
	v_add_co_u32_e32 v146, vcc, s97, v146
	v_add_u32_e32 v122, s34, v122
	s_nop 1
	v_cvt_pk_bf16_f32 v120, v218, s0
	v_addc_co_u32_e32 v147, vcc, 0, v147, vcc
	v_ashrrev_i32_e32 v123, 31, v122
	v_mfma_f32_16x16x32_bf16 v[214:217], v[222:225], v[116:119], v[214:217]
	global_store_short v[146:147], v120, off
	v_lshl_add_u64 v[146:147], s[36:37], 0, v[122:123]
	v_lshlrev_b64 v[146:147], 13, v[146:147]
	v_lshl_add_u64 v[146:147], s[28:29], 0, v[146:147]
	v_lshl_add_u64 v[146:147], v[146:147], 0, s[42:43]
	s_nop 2
	v_cvt_pk_bf16_f32 v120, v214, s0
	v_lshl_add_u64 v[146:147], v[146:147], 0, v[2:3]
	global_store_short v[160:161], v120, off offset:32
	v_lshl_add_u64 v[160:161], v[146:147], 0, s[78:79]
	v_add_co_u32_e32 v146, vcc, s97, v146
	v_add_u32_e32 v122, s34, v122
	v_cvt_pk_bf16_f32 v120, v219, s0
	v_addc_co_u32_e32 v147, vcc, 0, v147, vcc
	v_ashrrev_i32_e32 v123, 31, v122
	global_store_short v[146:147], v120, off
	v_lshl_add_u64 v[146:147], s[36:37], 0, v[122:123]
	v_lshlrev_b64 v[146:147], 13, v[146:147]
	v_lshl_add_u64 v[146:147], s[28:29], 0, v[146:147]
	v_lshl_add_u64 v[146:147], v[146:147], 0, s[42:43]
	v_cvt_pk_bf16_f32 v120, v215, s0
	v_lshl_add_u64 v[146:147], v[146:147], 0, v[2:3]
	global_store_short v[160:161], v120, off offset:32
	v_lshl_add_u64 v[160:161], v[146:147], 0, s[78:79]
	v_add_co_u32_e32 v146, vcc, s97, v146
	v_add_u32_e32 v122, s34, v122
	v_cvt_pk_bf16_f32 v120, v220, s0
	v_addc_co_u32_e32 v147, vcc, 0, v147, vcc
	v_ashrrev_i32_e32 v123, 31, v122
	global_store_short v[146:147], v120, off
	v_lshl_add_u64 v[146:147], s[36:37], 0, v[122:123]
	v_lshlrev_b64 v[146:147], 13, v[146:147]
	v_lshl_add_u64 v[146:147], s[28:29], 0, v[146:147]
	v_lshl_add_u64 v[146:147], v[146:147], 0, s[42:43]
	v_cvt_pk_bf16_f32 v120, v216, s0
	v_lshl_add_u64 v[146:147], v[146:147], 0, v[2:3]
	global_store_short v[160:161], v120, off offset:32
	v_lshl_add_u64 v[160:161], v[146:147], 0, s[78:79]
	v_add_co_u32_e32 v146, vcc, s97, v146
	v_cvt_pk_bf16_f32 v120, v221, s0
	s_nop 0
	v_addc_co_u32_e32 v147, vcc, 0, v147, vcc
	global_store_short v[146:147], v120, off
	v_cvt_pk_bf16_f32 v120, v217, s0
	v_or_b32_e32 v123, 48, v212
	global_store_short v[160:161], v120, off offset:32
	v_mad_u32_u24 v120, v123, s33, v144
	ds_read_b128 v[214:217], v120 offset:53248
	ds_read_b128 v[218:221], v142 offset:62464
	ds_read_b128 v[222:225], v142 offset:64768
	s_waitcnt lgkmcnt(1)
; #define LAS __attribute__((address_space(3)))
; DI unsigned short f2bf(float f) { return (unsigned short)(cvtpk(f, f) & 0xffffu); }
; #define MFMA16(a, b, c) __builtin_amdgcn_mfma_f32_16x16x32_bf16((a), (b), (c), 0, 0, 0)
; DI void gla_scan_phase(const PZ& p, LAS unsigned char* lds, int tid, int wave, int lane_in) {
;     ...
;             for (int mt = 0; mt < 4; ++mt) {
;                 f32x4 oacc[2]; oacc[0] = (f32x4){0.f, 0.f, 0.f, 0.f}; oacc[1] = oacc[0];
; #pragma unroll
;                 for (int ks = 0; ks < 2; ++ks) {
;                     const bf16x8 a = *(const LAS bf16x8*)(Ab + (mt * 16 + l15) * 72 + ks * 32 + g * 8);
; #pragma unroll
;                     for (int n2 = 0; n2 < 2; ++n2) { const bf16x8 bfr = *(const LAS bf16x8*)(Vt + (wave * 32 + n2 * 16 + l15) * 72 + ks * 32 + g * 8); oacc[n2] = MFMA16(a, bfr, oacc[n2]); }
;                 }
; #pragma unroll
;                 for (int kp = 0; kp < 4; ++kp) {
;                     const bf16x8 a = mk8(*(const LAS u32x2*)(Qd + (mt * 16 + l15) * 136 + (2 * kp) * 16 + g * 4), *(const LAS u32x2*)(Qd + (mt * 16 + l15) * 136 + (2 * kp + 1) * 16 + g * 4));
; #pragma unroll
;                     for (int n2 = 0; n2 < 2; ++n2) oacc[n2] = MFMA16(a, sfr[kp][n2], oacc[n2]);
;                 }
; #pragma unroll
;                 for (int j = 0; j < 4; ++j) {
;                     const long m = mc0 + sgn * (mt * 16 + g * 4 + j);
; #pragma unroll
;                     for (int n2 = 0; n2 < 2; ++n2) big[m * 4096 + ocol0 + wave * 32 + n2 * 16 + l15] = f2bf(oacc[n2][j]);
;                 }
;             }
; #pragma unroll
;             for (int md = 0; md < 8; ++md) {
;                 const f32x4 dv = *(const LAS f32x4*)(dc + md * 16 + g * 4);
;                 S[md][0] *= dv; S[md][1] *= dv;
; #pragma unroll
;                 for (int ks = 0; ks < 2; ++ks) {
;                     const bf16x8 a = *(const LAS bf16x8*)(KeT + (md * 16 + l15) * 72 + ks * 32 + g * 8);
; #pragma unroll
;                     for (int n2 = 0; n2 < 2; ++n2) { const bf16x8 bfr = *(const LAS bf16x8*)(Vt + (wave * 32 + n2 * 16 + l15) * 72 + ks * 32 + g * 8); S[md][n2] = MFMA16(a, bfr, S[md][n2]); }
	v_mfma_f32_16x16x32_bf16 v[218:221], v[214:217], v[218:221], 0
	v_mul_u32_u24_e32 v123, 0x110, v123
	v_add3_u32 v123, 0, v123, v213
	s_waitcnt lgkmcnt(0)
	v_mfma_f32_16x16x32_bf16 v[214:217], v[214:217], v[222:225], 0
	ds_read_b128 v[222:225], v120 offset:53312
	ds_read_b128 v[226:229], v142 offset:62528
	s_waitcnt lgkmcnt(0)
	v_mfma_f32_16x16x32_bf16 v[218:221], v[222:225], v[226:229], v[218:221]
	ds_read_b128 v[226:229], v142 offset:64832
	s_waitcnt lgkmcnt(0)
	v_mfma_f32_16x16x32_bf16 v[214:217], v[222:225], v[226:229], v[214:217]
	ds_read2_b64 v[222:225], v123 offset1:4
	s_waitcnt lgkmcnt(0)
	v_mfma_f32_16x16x32_bf16 v[92:95], v[222:225], v[92:95], v[214:217]
	s_nop 4
	ds_read2_b64 v[212:215], v123 offset0:8 offset1:12
	v_mfma_f32_16x16x32_bf16 v[88:91], v[222:225], v[88:91], v[218:221]
	s_waitcnt lgkmcnt(0)
	v_mfma_f32_16x16x32_bf16 v[88:91], v[212:215], v[96:99], v[88:91]
	ds_read2_b64 v[96:99], v123 offset0:16 offset1:20
	v_mfma_f32_16x16x32_bf16 v[92:95], v[212:215], v[100:103], v[92:95]
	s_waitcnt lgkmcnt(0)
	v_mfma_f32_16x16x32_bf16 v[88:91], v[96:99], v[104:107], v[88:91]
	v_mfma_f32_16x16x32_bf16 v[92:95], v[96:99], v[108:111], v[92:95]
	ds_read2_b64 v[96:99], v123 offset0:24 offset1:28
	s_waitcnt lgkmcnt(0)
	v_mfma_f32_16x16x32_bf16 v[88:91], v[96:99], v[112:115], v[88:91]
	s_nop 7
	v_cvt_pk_bf16_f32 v88, v88, s0
	v_mfma_f32_16x16x32_bf16 v[92:95], v[96:99], v[116:119], v[92:95]
	v_add_u32_e32 v96, s7, v122
	v_ashrrev_i32_e32 v97, 31, v96
	v_lshl_add_u64 v[98:99], s[36:37], 0, v[96:97]
	v_lshlrev_b64 v[98:99], 13, v[98:99]
	v_lshl_add_u64 v[98:99], s[28:29], 0, v[98:99]
	v_lshl_add_u64 v[98:99], v[98:99], 0, s[42:43]
	v_lshl_add_u64 v[98:99], v[98:99], 0, v[2:3]
	v_lshl_add_u64 v[100:101], v[98:99], 0, s[78:79]
	v_add_co_u32_e32 v98, vcc, s97, v98
	v_add_u32_e32 v96, s34, v96
	s_nop 0
	v_addc_co_u32_e32 v99, vcc, 0, v99, vcc
	v_ashrrev_i32_e32 v97, 31, v96
	global_store_short v[98:99], v88, off
	v_lshl_add_u64 v[98:99], s[36:37], 0, v[96:97]
	v_lshlrev_b64 v[98:99], 13, v[98:99]
	v_lshl_add_u64 v[98:99], s[28:29], 0, v[98:99]
	v_lshl_add_u64 v[98:99], v[98:99], 0, s[42:43]
	v_cvt_pk_bf16_f32 v88, v92, s0
	v_lshl_add_u64 v[98:99], v[98:99], 0, v[2:3]
	global_store_short v[100:101], v88, off offset:32
	v_add_co_u32_e32 v88, vcc, s97, v98
	v_cvt_pk_bf16_f32 v92, v89, s0
	s_nop 0
	v_addc_co_u32_e32 v89, vcc, 0, v99, vcc
	v_lshl_add_u64 v[100:101], v[98:99], 0, s[78:79]
	global_store_short v[88:89], v92, off
	v_cvt_pk_bf16_f32 v88, v93, s0
	global_store_short v[100:101], v88, off offset:32
	v_add_u32_e32 v88, s34, v96
	v_ashrrev_i32_e32 v89, 31, v88
	v_lshl_add_u64 v[92:93], s[36:37], 0, v[88:89]
	v_lshlrev_b64 v[92:93], 13, v[92:93]
	v_lshl_add_u64 v[92:93], s[28:29], 0, v[92:93]
	v_lshl_add_u64 v[92:93], v[92:93], 0, s[42:43]
	v_lshl_add_u64 v[92:93], v[92:93], 0, v[2:3]
	v_lshl_add_u64 v[96:97], v[92:93], 0, s[78:79]
	v_add_co_u32_e32 v92, vcc, s97, v92
	v_cvt_pk_bf16_f32 v89, v90, s0
	s_nop 0
	v_addc_co_u32_e32 v93, vcc, 0, v93, vcc
	global_store_short v[92:93], v89, off
	v_cvt_pk_bf16_f32 v89, v94, s0
	v_add_u32_e32 v88, s34, v88
	global_store_short v[96:97], v89, off offset:32
	v_ashrrev_i32_e32 v89, 31, v88
	v_lshl_add_u64 v[88:89], s[36:37], 0, v[88:89]
	v_lshlrev_b64 v[88:89], 13, v[88:89]
	v_lshl_add_u64 v[88:89], s[28:29], 0, v[88:89]
	v_lshl_add_u64 v[88:89], v[88:89], 0, s[42:43]
	v_lshl_add_u64 v[88:89], v[88:89], 0, v[2:3]
	v_lshl_add_u64 v[92:93], v[88:89], 0, s[78:79]
	v_add_co_u32_e32 v88, vcc, s97, v88
	v_cvt_pk_bf16_f32 v2, v91, s0
	s_nop 0
	v_addc_co_u32_e32 v89, vcc, 0, v89, vcc
	global_store_short v[88:89], v2, off
	v_cvt_pk_bf16_f32 v2, v95, s0
	global_store_short v[92:93], v2, off offset:32
	v_add_u32_e32 v2, 0x18c00, v144
	ds_read_b128 v[88:91], v2
	v_cmp_gt_i32_e32 vcc, s71, v198
	s_waitcnt lgkmcnt(0)
	v_pk_mul_f32 v[92:93], v[80:81], v[88:89]
	v_pk_mul_f32 v[94:95], v[82:83], v[90:91]
	v_pk_mul_f32 v[80:81], v[84:85], v[88:89]
	v_pk_mul_f32 v[82:83], v[86:87], v[90:91]
	ds_read_b128 v[84:87], v199 offset:34816
	ds_read_b128 v[88:91], v142 offset:62464
	s_waitcnt lgkmcnt(0)
	v_mfma_f32_16x16x32_bf16 v[100:103], v[84:87], v[88:91], v[92:95]
	s_nop 2
	ds_read_b128 v[92:95], v142 offset:64768
	ds_read_b128 v[104:107], v199 offset:34880
	ds_read_b128 v[96:99], v142 offset:62528
	s_waitcnt lgkmcnt(2)
	v_mfma_f32_16x16x32_bf16 v[84:87], v[84:87], v[92:95], v[80:83]
	s_waitcnt lgkmcnt(0)
	v_mfma_f32_16x16x32_bf16 v[80:83], v[104:107], v[96:99], v[100:103]
	s_nop 2
	ds_read_b128 v[100:103], v142 offset:64832
	s_waitcnt lgkmcnt(0)
	v_mfma_f32_16x16x32_bf16 v[84:87], v[104:107], v[100:103], v[84:87]
	ds_read_b128 v[104:107], v2 offset:64
	s_waitcnt lgkmcnt(0)
; #define LAS __attribute__((address_space(3)))
; #define MFMA16(a, b, c) __builtin_amdgcn_mfma_f32_16x16x32_bf16((a), (b), (c), 0, 0, 0)
; DI void gla_scan_phase(const PZ& p, LAS unsigned char* lds, int tid, int wave, int lane_in) {
;     ...
;             for (int md = 0; md < 8; ++md) {
;                 const f32x4 dv = *(const LAS f32x4*)(dc + md * 16 + g * 4);
;                 S[md][0] *= dv; S[md][1] *= dv;
; #pragma unroll
;                 for (int ks = 0; ks < 2; ++ks) {
;                     const bf16x8 a = *(const LAS bf16x8*)(KeT + (md * 16 + l15) * 72 + ks * 32 + g * 8);
; #pragma unroll
;                     for (int n2 = 0; n2 < 2; ++n2) { const bf16x8 bfr = *(const LAS bf16x8*)(Vt + (wave * 32 + n2 * 16 + l15) * 72 + ks * 32 + g * 8); S[md][n2] = MFMA16(a, bfr, S[md][n2]); }
;                 }
;             }
;             if (tv_ < 256) *(LAS f32x4*)(Tl + (tv_ >> 2) * 16 + (tv_ & 3) * 4) = tpre;
;             __syncthreads();
	v_pk_mul_f32 v[40:41], v[40:41], v[104:105]
	v_pk_mul_f32 v[42:43], v[42:43], v[106:107]
	v_pk_mul_f32 v[44:45], v[44:45], v[104:105]
	v_pk_mul_f32 v[46:47], v[46:47], v[106:107]
	ds_read_b128 v[104:107], v143 offset:34816
	s_waitcnt lgkmcnt(0)
	v_mfma_f32_16x16x32_bf16 v[40:43], v[104:107], v[88:91], v[40:43]
	v_mfma_f32_16x16x32_bf16 v[44:47], v[104:107], v[92:95], v[44:47]
	ds_read_b128 v[104:107], v143 offset:34880
	s_waitcnt lgkmcnt(0)
	v_mfma_f32_16x16x32_bf16 v[40:43], v[104:107], v[96:99], v[40:43]
	v_mfma_f32_16x16x32_bf16 v[44:47], v[104:107], v[100:103], v[44:47]
	ds_read_b128 v[104:107], v2 offset:128
	s_waitcnt lgkmcnt(0)
	v_pk_mul_f32 v[8:9], v[8:9], v[104:105]
	v_pk_mul_f32 v[10:11], v[10:11], v[106:107]
	v_pk_mul_f32 v[12:13], v[12:13], v[104:105]
	v_pk_mul_f32 v[14:15], v[14:15], v[106:107]
	ds_read_b128 v[104:107], v121 offset:34816
	s_waitcnt lgkmcnt(0)
	v_mfma_f32_16x16x32_bf16 v[8:11], v[104:107], v[88:91], v[8:11]
	v_mfma_f32_16x16x32_bf16 v[12:15], v[104:107], v[92:95], v[12:15]
	ds_read_b128 v[104:107], v121 offset:34880
	s_waitcnt lgkmcnt(0)
	v_mfma_f32_16x16x32_bf16 v[8:11], v[104:107], v[96:99], v[8:11]
	v_mfma_f32_16x16x32_bf16 v[12:15], v[104:107], v[100:103], v[12:15]
	ds_read_b128 v[104:107], v2 offset:192
	s_waitcnt lgkmcnt(0)
	v_pk_mul_f32 v[32:33], v[32:33], v[104:105]
	v_pk_mul_f32 v[34:35], v[34:35], v[106:107]
	v_pk_mul_f32 v[36:37], v[36:37], v[104:105]
	v_pk_mul_f32 v[38:39], v[38:39], v[106:107]
	ds_read_b128 v[104:107], v120 offset:34816
	s_waitcnt lgkmcnt(0)
	v_mfma_f32_16x16x32_bf16 v[32:35], v[104:107], v[88:91], v[32:35]
	v_mfma_f32_16x16x32_bf16 v[36:39], v[104:107], v[92:95], v[36:39]
	ds_read_b128 v[104:107], v120 offset:34880
	s_waitcnt lgkmcnt(0)
	v_mfma_f32_16x16x32_bf16 v[32:35], v[104:107], v[96:99], v[32:35]
	v_mfma_f32_16x16x32_bf16 v[36:39], v[104:107], v[100:103], v[36:39]
	ds_read_b128 v[104:107], v2 offset:256
	s_waitcnt lgkmcnt(0)
	v_pk_mul_f32 v[16:17], v[16:17], v[104:105]
	v_pk_mul_f32 v[18:19], v[18:19], v[106:107]
	v_pk_mul_f32 v[20:21], v[20:21], v[104:105]
	v_pk_mul_f32 v[22:23], v[22:23], v[106:107]
	ds_read_b128 v[104:107], v199 offset:44032
	s_waitcnt lgkmcnt(0)
	v_mfma_f32_16x16x32_bf16 v[16:19], v[104:107], v[88:91], v[16:19]
	v_mfma_f32_16x16x32_bf16 v[20:23], v[104:107], v[92:95], v[20:23]
	ds_read_b128 v[104:107], v199 offset:44096
	s_waitcnt lgkmcnt(0)
	v_mfma_f32_16x16x32_bf16 v[16:19], v[104:107], v[96:99], v[16:19]
	v_mfma_f32_16x16x32_bf16 v[20:23], v[104:107], v[100:103], v[20:23]
	ds_read_b128 v[104:107], v2 offset:320
	s_waitcnt lgkmcnt(0)
	v_pk_mul_f32 v[48:49], v[48:49], v[104:105]
	v_pk_mul_f32 v[50:51], v[50:51], v[106:107]
	v_pk_mul_f32 v[52:53], v[52:53], v[104:105]
	v_pk_mul_f32 v[54:55], v[54:55], v[106:107]
	ds_read_b128 v[104:107], v199 offset:46336
	s_waitcnt lgkmcnt(0)
	v_mfma_f32_16x16x32_bf16 v[48:51], v[104:107], v[88:91], v[48:51]
	v_mfma_f32_16x16x32_bf16 v[52:55], v[104:107], v[92:95], v[52:55]
	ds_read_b128 v[104:107], v199 offset:46400
	s_waitcnt lgkmcnt(0)
	v_mfma_f32_16x16x32_bf16 v[48:51], v[104:107], v[96:99], v[48:51]
	v_mfma_f32_16x16x32_bf16 v[52:55], v[104:107], v[100:103], v[52:55]
	ds_read_b128 v[104:107], v2 offset:384
	s_waitcnt lgkmcnt(0)
	v_pk_mul_f32 v[24:25], v[24:25], v[104:105]
	v_pk_mul_f32 v[26:27], v[26:27], v[106:107]
	v_pk_mul_f32 v[28:29], v[28:29], v[104:105]
	v_pk_mul_f32 v[30:31], v[30:31], v[106:107]
	ds_read_b128 v[104:107], v199 offset:48640
	s_waitcnt lgkmcnt(0)
	v_mfma_f32_16x16x32_bf16 v[24:27], v[104:107], v[88:91], v[24:27]
	v_mfma_f32_16x16x32_bf16 v[28:31], v[104:107], v[92:95], v[28:31]
	ds_read_b128 v[104:107], v199 offset:48704
	s_waitcnt lgkmcnt(0)
	v_mfma_f32_16x16x32_bf16 v[24:27], v[104:107], v[96:99], v[24:27]
	v_mfma_f32_16x16x32_bf16 v[28:31], v[104:107], v[100:103], v[28:31]
	ds_read_b128 v[104:107], v2 offset:448
	s_waitcnt lgkmcnt(0)
	v_pk_mul_f32 v[56:57], v[56:57], v[104:105]
	v_pk_mul_f32 v[58:59], v[58:59], v[106:107]
	v_pk_mul_f32 v[60:61], v[60:61], v[104:105]
	v_pk_mul_f32 v[62:63], v[62:63], v[106:107]
	ds_read_b128 v[104:107], v199 offset:50944
	s_waitcnt lgkmcnt(0)
	v_mfma_f32_16x16x32_bf16 v[56:59], v[104:107], v[88:91], v[56:59]
	ds_read_b128 v[88:91], v199 offset:51008
	v_mfma_f32_16x16x32_bf16 v[60:63], v[104:107], v[92:95], v[60:63]
	s_waitcnt lgkmcnt(0)
	v_mfma_f32_16x16x32_bf16 v[56:59], v[88:91], v[96:99], v[56:59]
	v_mfma_f32_16x16x32_bf16 v[60:63], v[88:91], v[100:103], v[60:63]
	s_and_saveexec_b64 s[36:37], vcc
	s_cbranch_execz .LBB0_115
	v_lshlrev_b32_e32 v2, 4, v198
	v_and_b32_e32 v88, 0xffffffc0, v2
	v_and_b32_e32 v2, 48, v2
	v_add3_u32 v2, s22, v88, v2
	ds_write_b128 v2, v[4:7]
	s_branch .LBB0_115
